# ret_out: the 8 S_prev^T fragment loads of the cross-chunk term issued before the unit's first barrier (registers idle after staging), MFMA operands renamed
# baseline (speedup 1.0000x reference)
.LBB0_195:
	s_or_b64 exec, exec, s[10:11]
	v_readlane_b32 s0, v254, 50
	s_waitcnt lgkmcnt(0)
	s_barrier
	v_mov_b32_e32 v0, s0
	ds_read_b32 v0, v0
	s_movk_i32 s0, 0x1ff
	s_mov_b64 s[10:11], -1
	s_waitcnt lgkmcnt(0)
	v_cmp_lt_i32_e32 vcc, s0, v0
	v_readfirstlane_b32 s71, v0
	s_cbranch_vccnz .LBB0_192
	v_readlane_b32 s12, v254, 25
	v_readlane_b32 s14, v254, 27
	v_readlane_b32 s15, v254, 28
	s_mov_b64 s[64:65], s[14:15]
	s_add_u32 s68, s64, 0xc700000
	s_addc_u32 s69, s65, 0
	s_ashr_i32 s10, s71, 6
	s_bfe_u32 s82, s71, 0x40002
	s_ashr_i32 s11, s10, 31
	s_lshl_b64 s[66:67], s[10:11], 11
	s_lshl_b32 s0, s82, 7
	s_or_b32 s80, s66, s0
	s_mul_i32 s66, s67, 0x2800
	s_mul_hi_u32 s0, s80, 0x2800
	s_and_b32 s81, s71, 3
	s_add_i32 s0, s0, s66
	s_mul_i32 s10, s80, 0x2800
	v_readlane_b32 s13, v254, 26
	s_add_u32 s12, s68, s10
	s_addc_u32 s13, s69, s0
	s_lshl_b32 s0, s81, 8
	s_add_u32 s14, s12, s0
	s_addc_u32 s15, s13, 0
	s_add_u32 s10, s14, 0x1000
	s_addc_u32 s11, s15, 0
	v_lshl_add_u64 v[0:1], s[10:11], 0, v[110:111]
	v_lshl_add_u64 v[0:1], v[0:1], 0, v[112:113]
	global_load_dwordx4 v[218:221], v[0:1], off
	v_add_u32_e32 v52, v77, v95
	v_lshl_add_u64 v[0:1], s[10:11], 0, v[114:115]
	v_lshl_add_u64 v[0:1], v[0:1], 0, v[116:117]
	global_load_dwordx4 v[222:225], v[0:1], off
	v_lshl_add_u64 v[0:1], s[10:11], 0, v[118:119]
	v_lshl_add_u64 v[0:1], v[0:1], 0, v[120:121]
	global_load_dwordx4 v[226:229], v[0:1], off
	v_lshl_add_u64 v[0:1], s[10:11], 0, v[122:123]
	v_lshl_add_u64 v[0:1], v[0:1], 0, v[124:125]
	global_load_dwordx4 v[230:233], v[0:1], off
	s_add_u32 s10, s14, 0x1400
	s_addc_u32 s11, s15, 0
	v_lshl_add_u64 v[0:1], s[10:11], 0, v[110:111]
	v_lshl_add_u64 v[0:1], v[0:1], 0, v[112:113]
	global_load_dwordx4 v[234:237], v[0:1], off
	v_lshl_add_u64 v[0:1], s[10:11], 0, v[114:115]
	v_lshl_add_u64 v[0:1], v[0:1], 0, v[116:117]
	global_load_dwordx4 v[238:241], v[0:1], off
	v_lshl_add_u64 v[0:1], s[10:11], 0, v[118:119]
	v_lshl_add_u64 v[0:1], v[0:1], 0, v[120:121]
	global_load_dwordx4 v[242:245], v[0:1], off
	v_lshl_add_u64 v[0:1], s[10:11], 0, v[122:123]
	v_lshl_add_u64 v[0:1], v[0:1], 0, v[124:125]
	global_load_dwordx4 v[246:249], v[0:1], off
	s_lshl_b32 s10, s81, 9
	s_add_u32 s10, s12, s10
	s_addc_u32 s11, s13, 0
	s_add_u32 s10, s10, 0x1800
	s_addc_u32 s11, s11, 0
	s_movk_i32 s12, 0x2000
	s_waitcnt vmcnt(0) lgkmcnt(0)
	ds_write_b128 v181, v[218:221]
	ds_write_b128 v193, v[222:225]
	ds_write_b128 v194, v[226:229]
	ds_write_b128 v195, v[230:233]
	ds_write_b128 v181, v[234:237] offset:34816
	ds_write_b128 v193, v[238:241] offset:34816
	ds_write_b128 v194, v[242:245] offset:34816
	ds_write_b128 v195, v[246:249] offset:34816
	v_lshl_add_u64 v[250:251], v[78:79], 1, s[10:11]
	v_lshl_add_u64 v[250:251], v[80:81], 1, v[250:251]
	global_load_dwordx4 v[218:221], v[250:251], off
	v_add_co_u32_e32 v250, vcc, s12, v250
	s_nop 1
	v_addc_co_u32_e32 v251, vcc, 0, v251, vcc
	global_load_dwordx4 v[222:225], v[250:251], off offset:2048
	v_lshl_add_u64 v[250:251], v[82:83], 1, s[10:11]
	v_lshl_add_u64 v[250:251], v[84:85], 1, v[250:251]
	global_load_dwordx4 v[226:229], v[250:251], off
	v_add_co_u32_e32 v250, vcc, s12, v250
	s_nop 1
	v_addc_co_u32_e32 v251, vcc, 0, v251, vcc
	global_load_dwordx4 v[230:233], v[250:251], off offset:2048
	v_lshl_add_u64 v[250:251], v[86:87], 1, s[10:11]
	v_lshl_add_u64 v[250:251], v[88:89], 1, v[250:251]
	global_load_dwordx4 v[234:237], v[250:251], off
	v_add_co_u32_e32 v250, vcc, s12, v250
	s_nop 1
	v_addc_co_u32_e32 v251, vcc, 0, v251, vcc
	global_load_dwordx4 v[238:241], v[250:251], off offset:2048
	v_lshl_add_u64 v[250:251], v[90:91], 1, s[10:11]
	v_lshl_add_u64 v[250:251], v[92:93], 1, v[250:251]
	global_load_dwordx4 v[242:245], v[250:251], off
	v_add_co_u32_e32 v250, vcc, s12, v250
	s_nop 1
	v_addc_co_u32_e32 v251, vcc, 0, v251, vcc
	global_load_dwordx4 v[246:249], v[250:251], off offset:2048
	s_waitcnt vmcnt(0)
	v_mov_b32_e32 v0, v218
	v_mov_b32_e32 v1, v219
	v_mov_b32_e32 v2, v220
	v_mov_b32_e32 v3, v221
	v_and_b32_e32 v8, 0xffff, v0
	v_mov_b32_e32 v4, v222
	v_mov_b32_e32 v5, v223
	v_mov_b32_e32 v6, v224
	v_mov_b32_e32 v7, v225
	v_lshrrev_b32_e32 v0, 16, v0
	v_lshl_or_b32 v8, v4, 16, v8
	v_and_or_b32 v0, v4, s59, v0
	ds_write2_b32 v196, v8, v0 offset1:68
	v_and_b32_e32 v0, 0xffff, v1
	v_lshrrev_b32_e32 v1, 16, v1
	v_lshl_or_b32 v0, v5, 16, v0
	v_and_or_b32 v1, v5, s59, v1
	ds_write2_b32 v196, v0, v1 offset0:136 offset1:204
	v_and_b32_e32 v0, 0xffff, v2
	v_lshrrev_b32_e32 v1, 16, v2
	v_lshl_or_b32 v0, v6, 16, v0
	v_and_or_b32 v1, v6, s59, v1
	v_add_u32_e32 v2, 0x400, v196
	ds_write2_b32 v2, v0, v1 offset0:16 offset1:84
	v_and_b32_e32 v0, 0xffff, v3
	v_lshrrev_b32_e32 v1, 16, v3
	v_lshl_or_b32 v0, v7, 16, v0
	v_and_or_b32 v1, v7, s59, v1
	ds_write2_b32 v2, v0, v1 offset0:152 offset1:220
	v_mov_b32_e32 v0, v226
	v_mov_b32_e32 v1, v227
	v_mov_b32_e32 v2, v228
	v_mov_b32_e32 v3, v229
	v_and_b32_e32 v8, 0xffff, v0
	v_mov_b32_e32 v4, v230
	v_mov_b32_e32 v5, v231
	v_mov_b32_e32 v6, v232
	v_mov_b32_e32 v7, v233
	v_lshrrev_b32_e32 v0, 16, v0
	v_lshl_or_b32 v8, v4, 16, v8
	v_and_or_b32 v0, v4, s59, v0
	ds_write2_b32 v197, v8, v0 offset1:68
	v_and_b32_e32 v0, 0xffff, v1
	v_lshrrev_b32_e32 v1, 16, v1
	v_lshl_or_b32 v0, v5, 16, v0
	v_and_or_b32 v1, v5, s59, v1
	ds_write2_b32 v197, v0, v1 offset0:136 offset1:204
	v_and_b32_e32 v0, 0xffff, v2
	v_lshrrev_b32_e32 v1, 16, v2
	v_lshl_or_b32 v0, v6, 16, v0
	v_and_or_b32 v1, v6, s59, v1
	v_add_u32_e32 v2, 0x400, v197
	ds_write2_b32 v2, v0, v1 offset0:16 offset1:84
	v_and_b32_e32 v0, 0xffff, v3
	v_lshrrev_b32_e32 v1, 16, v3
	v_lshl_or_b32 v0, v7, 16, v0
	v_and_or_b32 v1, v7, s59, v1
	ds_write2_b32 v2, v0, v1 offset0:152 offset1:220
	v_mov_b32_e32 v0, v234
	v_mov_b32_e32 v1, v235
	v_mov_b32_e32 v2, v236
	v_mov_b32_e32 v3, v237
	v_and_b32_e32 v8, 0xffff, v0
	v_mov_b32_e32 v4, v238
	v_mov_b32_e32 v5, v239
	v_mov_b32_e32 v6, v240
	v_mov_b32_e32 v7, v241
	v_lshrrev_b32_e32 v0, 16, v0
	v_lshl_or_b32 v8, v4, 16, v8
	v_and_or_b32 v0, v4, s59, v0
	ds_write2_b32 v198, v8, v0 offset1:68
	v_and_b32_e32 v0, 0xffff, v1
	v_lshrrev_b32_e32 v1, 16, v1
	v_lshl_or_b32 v0, v5, 16, v0
	v_and_or_b32 v1, v5, s59, v1
	ds_write2_b32 v198, v0, v1 offset0:136 offset1:204
	v_and_b32_e32 v0, 0xffff, v2
	v_lshrrev_b32_e32 v1, 16, v2
	v_lshl_or_b32 v0, v6, 16, v0
	v_and_or_b32 v1, v6, s59, v1
	v_add_u32_e32 v2, 0x400, v198
	ds_write2_b32 v2, v0, v1 offset0:16 offset1:84
	v_and_b32_e32 v0, 0xffff, v3
	v_lshrrev_b32_e32 v1, 16, v3
	v_lshl_or_b32 v0, v7, 16, v0
	v_and_or_b32 v1, v7, s59, v1
	ds_write2_b32 v2, v0, v1 offset0:152 offset1:220
	v_mov_b32_e32 v0, v242
	v_mov_b32_e32 v1, v243
	v_mov_b32_e32 v2, v244
	v_mov_b32_e32 v3, v245
	v_and_b32_e32 v8, 0xffff, v0
	v_mov_b32_e32 v4, v246
	v_mov_b32_e32 v5, v247
	v_mov_b32_e32 v6, v248
	v_mov_b32_e32 v7, v249
	v_lshrrev_b32_e32 v0, 16, v0
	s_andn2_b64 vcc, exec, s[6:7]
	v_lshl_or_b32 v8, v4, 16, v8
	v_and_or_b32 v0, v4, s59, v0
	ds_write2_b32 v199, v8, v0 offset1:68
	v_and_b32_e32 v0, 0xffff, v1
	v_lshrrev_b32_e32 v1, 16, v1
	v_lshl_or_b32 v0, v5, 16, v0
	v_and_or_b32 v1, v5, s59, v1
	ds_write2_b32 v199, v0, v1 offset0:136 offset1:204
	v_and_b32_e32 v0, 0xffff, v2
	v_lshrrev_b32_e32 v1, 16, v2
	v_lshl_or_b32 v0, v6, 16, v0
	v_and_or_b32 v1, v6, s59, v1
	v_add_u32_e32 v2, 0x400, v199
	ds_write2_b32 v2, v0, v1 offset0:16 offset1:84
	v_and_b32_e32 v0, 0xffff, v3
	v_lshrrev_b32_e32 v1, 16, v3
	v_lshl_or_b32 v0, v7, 16, v0
	v_and_or_b32 v1, v7, s59, v1
	ds_write2_b32 v2, v0, v1 offset0:152 offset1:220
	s_lshl_b32 s10, s71, 16
	s_add_u32 s10, s64, s10
	s_addc_u32 s11, s65, 0
	v_lshl_add_u64 v[250:251], v[108:109], 1, s[10:11]
	v_lshl_add_u64 v[250:251], v[250:251], 0, v[152:153]
	s_mov_b32 s10, 0x1d700000
	s_mov_b32 s11, 0
	v_lshl_add_u64 v[250:251], v[250:251], 0, s[10:11]
	global_load_dwordx4 v[218:221], v[250:251], off
	global_load_dwordx4 v[222:225], v[250:251], off offset:64
	global_load_dwordx4 v[226:229], v[250:251], off offset:128
	global_load_dwordx4 v[230:233], v[250:251], off offset:192
	s_movk_i32 s10, 0x1000
	v_lshl_add_u64 v[250:251], v[250:251], 0, s[10:11]
	global_load_dwordx4 v[234:237], v[250:251], off
	global_load_dwordx4 v[238:241], v[250:251], off offset:64
	global_load_dwordx4 v[242:245], v[250:251], off offset:128
	global_load_dwordx4 v[246:249], v[250:251], off offset:192
	s_waitcnt lgkmcnt(0)
	s_barrier
	ds_read_b128 v[0:3], v201 offset:34816
	v_cndmask_b32_e64 v4, 0, 1, s[6:7]
	v_cmp_ne_u32_e64 s[10:11], 1, v4
	s_cbranch_vccnz .LBB0_200
	ds_read_b128 v[4:7], v52
	s_waitcnt lgkmcnt(0)
	v_mfma_f32_16x16x32_bf16 v[28:31], v[0:3], v[4:7], 0
	v_cndmask_b32_e64 v4, 0, 1, s[8:9]
	v_cmp_ne_u32_e64 s[12:13], 1, v4
	s_andn2_b64 vcc, exec, s[8:9]
	s_cbranch_vccz .LBB0_201

.LBB0_240:
	s_waitcnt lgkmcnt(0)
	v_sub_f32_e32 v32, 0xc0a00000, v36
	v_exp_f32_e32 v32, v32
	s_mov_b32 s10, 0x800000
	s_barrier
	v_sub_f32_e32 v32, 1.0, v32
	v_cmp_gt_f32_e32 vcc, s10, v32
	s_and_b64 s[10:11], vcc, exec
	s_cselect_b32 s10, 32, 0
	v_ldexp_f32 v32, v32, s10
	v_log_f32_e32 v32, v32
	v_cndmask_b32_e32 v33, 0, v155, vcc
	v_readlane_b32 s10, v255, 10
	v_readlane_b32 s11, v255, 11
	v_sub_f32_e32 v204, v32, v33
	v_mul_f32_e32 v32, v204, v103
	v_exp_f32_e32 v35, v32
	v_mul_f32_e32 v33, v204, v105
	v_mul_f32_e32 v34, v204, v107
	v_mul_f32_e32 v36, v204, v128
	v_exp_f32_e32 v37, v33
	v_exp_f32_e32 v32, v34
	v_exp_f32_e32 v33, v36
	v_mul_f32_e32 v28, v35, v28
	v_cndmask_b32_e64 v34, v28, 0, s[10:11]
	v_readlane_b32 s10, v255, 12
	v_mul_f32_e32 v28, v37, v29
	v_readlane_b32 s11, v255, 13
	v_readlane_b32 s12, v255, 18
	s_nop 0
	v_cndmask_b32_e64 v35, 0, v28, s[10:11]
	v_pk_mul_f32 v[28:29], v[32:33], v[30:31]
	v_readlane_b32 s10, v255, 16
	v_cvt_pk_bf16_f32 v28, v28, v29
	v_readlane_b32 s11, v255, 17
	v_mul_f32_e32 v31, v204, v129
	v_cvt_pk_bf16_f32 v30, v34, v35
	v_cndmask_b32_e64 v29, v28, 0, s[10:11]
	v_readlane_b32 s10, v255, 14
	v_lshrrev_b32_e32 v28, 16, v28
	v_readlane_b32 s11, v255, 15
	v_exp_f32_e32 v32, v31
	v_readlane_b32 s13, v255, 19
	v_cndmask_b32_e64 v28, v28, 0, s[10:11]
	s_mov_b32 s10, 0x5040100
	v_perm_b32 v31, v28, v29, s10
	v_add_u32_e32 v28, v101, v95
	ds_write_b64 v28, v[30:31] offset:34816
	v_mul_f32_e32 v28, v204, v130
	v_exp_f32_e32 v30, v28
	v_mul_f32_e32 v28, v204, v131
	v_mul_f32_e32 v29, v204, v132
	v_exp_f32_e32 v28, v28
	v_exp_f32_e32 v29, v29
	v_mul_f32_e32 v24, v32, v24
	v_cndmask_b32_e64 v31, v24, 0, s[12:13]
	v_readlane_b32 s12, v255, 20
	v_mul_f32_e32 v24, v30, v25
	v_readlane_b32 s13, v255, 21
	s_andn2_b32 s71, s71, 63
	v_add_u32_e32 v205, v77, v133
	v_cndmask_b32_e64 v30, 0, v24, s[12:13]
	v_pk_mul_f32 v[24:25], v[28:29], v[26:27]
	v_readlane_b32 s12, v255, 24
	v_cvt_pk_bf16_f32 v24, v24, v25
	v_readlane_b32 s13, v255, 25
	v_mul_f32_e32 v27, v204, v134
	v_exp_f32_e32 v28, v27
	v_cndmask_b32_e64 v25, v24, 0, s[12:13]
	v_readlane_b32 s12, v255, 22
	v_lshrrev_b32_e32 v24, 16, v24
	v_readlane_b32 s13, v255, 23
	v_cvt_pk_bf16_f32 v26, v31, v30
	v_add_u32_e32 v29, v101, v133
	v_cndmask_b32_e64 v24, v24, 0, s[12:13]
	v_perm_b32 v27, v24, v25, s10
	v_mul_f32_e32 v24, v204, v135
	ds_write_b64 v29, v[26:27] offset:34816
	v_exp_f32_e32 v26, v24
	v_mul_f32_e32 v24, v204, v136
	v_mul_f32_e32 v25, v204, v137
	v_exp_f32_e32 v24, v24
	v_exp_f32_e32 v25, v25
	v_readlane_b32 s12, v255, 26
	v_mul_f32_e32 v20, v28, v20
	v_readlane_b32 s13, v255, 27
	v_mul_f32_e32 v53, v204, v180
	s_nop 0
	v_cndmask_b32_e64 v27, v20, 0, s[12:13]
	v_readlane_b32 s12, v255, 28
	v_mul_f32_e32 v20, v26, v21
	v_readlane_b32 s13, v255, 29
	s_nop 1
	v_cndmask_b32_e64 v26, 0, v20, s[12:13]
	v_pk_mul_f32 v[20:21], v[24:25], v[22:23]
	v_readlane_b32 s12, v255, 32
	v_cvt_pk_bf16_f32 v20, v20, v21
	v_readlane_b32 s13, v255, 33
	v_mul_f32_e32 v23, v204, v138
	v_exp_f32_e32 v24, v23
	v_cndmask_b32_e64 v21, v20, 0, s[12:13]
	v_readlane_b32 s12, v255, 30
	v_lshrrev_b32_e32 v20, 16, v20
	v_readlane_b32 s13, v255, 31
	v_cvt_pk_bf16_f32 v22, v27, v26
	v_mul_f32_e32 v16, v24, v16
	v_cndmask_b32_e64 v20, v20, 0, s[12:13]
	v_perm_b32 v23, v20, v21, s10
	v_mul_f32_e32 v20, v204, v139
	ds_write_b64 v29, v[22:23] offset:39168
	v_exp_f32_e32 v22, v20
	v_mul_f32_e32 v20, v204, v140
	v_mul_f32_e32 v21, v204, v141
	v_exp_f32_e32 v20, v20
	v_exp_f32_e32 v21, v21
	v_readlane_b32 s12, v254, 61
	v_readlane_b32 s13, v254, 62
	s_nop 1
	v_cndmask_b32_e64 v23, v16, 0, s[12:13]
	v_readlane_b32 s12, v255, 0
	v_mul_f32_e32 v16, v22, v17
	v_readlane_b32 s13, v255, 1
	s_nop 1
	v_cndmask_b32_e64 v22, 0, v16, s[12:13]
	v_pk_mul_f32 v[16:17], v[20:21], v[18:19]
	v_readlane_b32 s12, v255, 4
	v_cvt_pk_bf16_f32 v16, v16, v17
	v_readlane_b32 s13, v255, 5
	v_mul_f32_e32 v19, v204, v142
	v_cvt_pk_bf16_f32 v18, v23, v22
	v_cndmask_b32_e64 v17, v16, 0, s[12:13]
	v_readlane_b32 s12, v255, 2
	v_lshrrev_b32_e32 v16, 16, v16
	v_readlane_b32 s13, v255, 3
	v_exp_f32_e32 v20, v19
	s_nop 0
	v_cndmask_b32_e64 v16, v16, 0, s[12:13]
	v_perm_b32 v19, v16, v17, s10
	v_add_u32_e32 v16, v101, v97
	ds_write_b64 v16, v[18:19] offset:34816
	v_mul_f32_e32 v16, v204, v143
	v_exp_f32_e32 v18, v16
	v_mul_f32_e32 v16, v204, v144
	v_mul_f32_e32 v17, v204, v145
	v_exp_f32_e32 v16, v16
	v_exp_f32_e32 v17, v17
	v_readlane_b32 s12, v255, 6
	v_mul_f32_e32 v12, v20, v12
	v_readlane_b32 s13, v255, 7
	s_nop 1
	v_cndmask_b32_e64 v19, v12, 0, s[12:13]
	v_readlane_b32 s12, v255, 8
	v_mul_f32_e32 v12, v18, v13
	v_readlane_b32 s13, v255, 9
	s_nop 1
	v_cndmask_b32_e64 v18, 0, v12, s[12:13]
	v_pk_mul_f32 v[12:13], v[16:17], v[14:15]
	v_readlane_b32 s12, v255, 36
	v_cvt_pk_bf16_f32 v12, v12, v13
	v_readlane_b32 s13, v255, 37
	v_mul_f32_e32 v15, v204, v146
	v_exp_f32_e32 v16, v15
	v_cndmask_b32_e64 v13, v12, 0, s[12:13]
	v_readlane_b32 s12, v255, 34
	v_lshrrev_b32_e32 v12, 16, v12
	v_readlane_b32 s13, v255, 35
	v_cvt_pk_bf16_f32 v14, v19, v18
	v_mul_f32_e32 v8, v16, v8
	v_cndmask_b32_e64 v12, v12, 0, s[12:13]
	v_perm_b32 v15, v12, v13, s10
	v_mul_f32_e32 v12, v204, v147
	ds_write_b64 v29, v[14:15] offset:47872
	v_exp_f32_e32 v14, v12
	v_mul_f32_e32 v12, v204, v148
	v_mul_f32_e32 v13, v204, v149
	v_exp_f32_e32 v12, v12
	v_exp_f32_e32 v13, v13
	v_readlane_b32 s12, v255, 38
	v_readlane_b32 s13, v255, 39
	s_nop 1
	v_cndmask_b32_e64 v15, v8, 0, s[12:13]
	v_readlane_b32 s12, v255, 40
	v_mul_f32_e32 v8, v14, v9
	v_readlane_b32 s13, v255, 41
	s_nop 1
	v_cndmask_b32_e64 v14, 0, v8, s[12:13]
	v_pk_mul_f32 v[8:9], v[12:13], v[10:11]
	v_readlane_b32 s12, v255, 44
	v_cvt_pk_bf16_f32 v8, v8, v9
	v_readlane_b32 s13, v255, 45
	v_mul_f32_e32 v11, v204, v150
	v_exp_f32_e32 v12, v11
	v_cndmask_b32_e64 v9, v8, 0, s[12:13]
	v_readlane_b32 s12, v255, 42
	v_lshrrev_b32_e32 v8, 16, v8
	v_readlane_b32 s13, v255, 43
	v_cvt_pk_bf16_f32 v10, v15, v14
	v_mul_f32_e32 v4, v12, v4
	v_cndmask_b32_e64 v8, v8, 0, s[12:13]
	v_perm_b32 v11, v8, v9, s10
	v_mul_f32_e32 v8, v204, v151
	ds_write_b64 v29, v[10:11] offset:52224
	v_exp_f32_e32 v10, v8
	v_mul_f32_e32 v8, v204, v158
	v_mul_f32_e32 v9, v204, v159
	v_exp_f32_e32 v8, v8
	v_exp_f32_e32 v9, v9
	v_readlane_b32 s12, v255, 46
	v_readlane_b32 s13, v255, 47
	s_nop 1
	v_cndmask_b32_e64 v11, v4, 0, s[12:13]
	v_readlane_b32 s12, v255, 48
	v_mul_f32_e32 v4, v10, v5
	v_readlane_b32 s13, v255, 49
	s_nop 1
	v_cndmask_b32_e64 v10, 0, v4, s[12:13]
	v_pk_mul_f32 v[4:5], v[8:9], v[6:7]
	v_mul_f32_e32 v7, v204, v160
	v_cvt_pk_bf16_f32 v4, v4, v5
	v_cndmask_b32_e64 v5, v4, 0, s[86:87]
	v_lshrrev_b32_e32 v4, 16, v4
	v_cndmask_b32_e64 v4, v4, 0, s[84:85]
	v_cvt_pk_bf16_f32 v6, v11, v10
	v_exp_f32_e32 v8, v7
	v_perm_b32 v7, v4, v5, s10
	v_mul_f32_e32 v4, v204, v161
	ds_write_b64 v29, v[6:7] offset:56576
	v_exp_f32_e32 v6, v4
	v_mul_f32_e32 v4, v204, v162
	v_mul_f32_e32 v5, v204, v172
	v_exp_f32_e32 v4, v4
	v_exp_f32_e32 v5, v5
	v_mul_f32_e32 v0, v8, v0
	v_cndmask_b32_e64 v7, v0, 0, s[88:89]
	v_mul_f32_e32 v0, v6, v1
	v_cndmask_b32_e64 v6, 0, v0, s[90:91]
	v_pk_mul_f32 v[0:1], v[4:5], v[2:3]
	v_cvt_pk_bf16_f32 v2, v7, v6
	v_cvt_pk_bf16_f32 v0, v0, v1
	v_cndmask_b32_e64 v1, v0, 0, s[94:95]
	v_lshrrev_b32_e32 v0, 16, v0
	v_cndmask_b32_e64 v0, v0, 0, s[92:93]
	v_perm_b32 v3, v0, v1, s10
	s_lshl_b32 s10, s82, 2
	s_or_b32 s10, s10, s71
	s_or_b32 s10, s10, s81
	s_ashr_i32 s11, s10, 31
	s_lshl_b64 s[10:11], s[10:11], 16
	s_add_u32 s10, s64, s10
	v_add_u32_e32 v0, v101, v99
	s_addc_u32 s11, s65, s11
	ds_write_b64 v0, v[2:3] offset:34816
	v_lshl_add_u64 v[0:1], v[108:109], 1, s[10:11]
	v_lshl_add_u64 v[74:75], v[0:1], 0, v[152:153]
	s_mov_b32 s10, 0x1d700000
	v_add_co_u32_e32 v0, vcc, s10, v74
	s_mov_b32 s10, 0x1d701000
	s_nop 0
	v_addc_co_u32_e32 v1, vcc, 0, v75, vcc
	v_add_co_u32_e32 v12, vcc, s10, v74
	s_nop 0
	v_addc_co_u32_e32 v13, vcc, 0, v75, vcc
	ds_read_b128 v[4:7], v52
	ds_read_b128 v[70:73], v202
	s_waitcnt vmcnt(0) lgkmcnt(0)
	v_mfma_f32_16x16x32_bf16 v[8:11], v[218:221], v[4:7], 0
	s_mov_b64 s[10:11], 0x1d700000
	ds_read_b128 v[214:217], v202 offset:128
	v_mfma_f32_16x16x32_bf16 v[16:19], v[234:237], v[4:7], 0
	ds_read_b128 v[4:7], v205
	s_waitcnt lgkmcnt(0)
	v_mfma_f32_16x16x32_bf16 v[20:23], v[218:221], v[4:7], 0
	v_mfma_f32_16x16x32_bf16 v[24:27], v[234:237], v[4:7], 0
	ds_read_b128 v[4:7], v205 offset:4352
	s_waitcnt lgkmcnt(0)
	v_mfma_f32_16x16x32_bf16 v[28:31], v[218:221], v[4:7], 0
	v_mfma_f32_16x16x32_bf16 v[32:35], v[234:237], v[4:7], 0
	ds_read_b128 v[4:7], v203
	s_waitcnt lgkmcnt(0)
	v_mfma_f32_16x16x32_bf16 v[36:39], v[218:221], v[4:7], 0
	v_mfma_f32_16x16x32_bf16 v[40:43], v[234:237], v[4:7], 0
	ds_read_b128 v[4:7], v205 offset:13056
	s_waitcnt lgkmcnt(0)
	v_mfma_f32_16x16x32_bf16 v[44:47], v[218:221], v[4:7], 0
	v_mfma_f32_16x16x32_bf16 v[48:51], v[234:237], v[4:7], 0
	ds_read_b128 v[4:7], v205 offset:17408
	s_waitcnt lgkmcnt(0)
	v_mfma_f32_16x16x32_bf16 v[54:57], v[218:221], v[4:7], 0
	v_mfma_f32_16x16x32_bf16 v[58:61], v[234:237], v[4:7], 0
	ds_read_b128 v[4:7], v205 offset:21760
	s_waitcnt lgkmcnt(0)
	v_mfma_f32_16x16x32_bf16 v[62:65], v[218:221], v[4:7], 0
	v_mfma_f32_16x16x32_bf16 v[66:69], v[234:237], v[4:7], 0
	v_lshl_add_u64 v[4:5], v[74:75], 0, s[10:11]
	s_mov_b64 s[10:11], 0x1d701000
	v_lshl_add_u64 v[6:7], v[74:75], 0, s[10:11]
	v_mfma_f32_16x16x32_bf16 v[206:209], v[218:221], v[70:73], 0
	v_mfma_f32_16x16x32_bf16 v[0:3], v[234:237], v[70:73], 0
	ds_read_b128 v[12:15], v52 offset:64
	s_waitcnt vmcnt(0) lgkmcnt(0)
	v_mfma_f32_16x16x32_bf16 v[8:11], v[222:225], v[12:15], v[8:11]
	v_mfma_f32_16x16x32_bf16 v[12:15], v[238:241], v[12:15], v[16:19]
	s_nop 2
	ds_read_b128 v[16:19], v205 offset:64
	s_waitcnt lgkmcnt(0)
	v_mfma_f32_16x16x32_bf16 v[20:23], v[222:225], v[16:19], v[20:23]
	v_mfma_f32_16x16x32_bf16 v[16:19], v[238:241], v[16:19], v[24:27]
	s_nop 2
	ds_read_b128 v[24:27], v205 offset:4416
	s_waitcnt lgkmcnt(0)
	v_mfma_f32_16x16x32_bf16 v[28:31], v[222:225], v[24:27], v[28:31]
	v_mfma_f32_16x16x32_bf16 v[24:27], v[238:241], v[24:27], v[32:35]
	s_nop 2
	ds_read_b128 v[32:35], v203 offset:64
	s_waitcnt lgkmcnt(0)
	v_mfma_f32_16x16x32_bf16 v[36:39], v[222:225], v[32:35], v[36:39]
	v_mfma_f32_16x16x32_bf16 v[32:35], v[238:241], v[32:35], v[40:43]
	s_nop 2
	ds_read_b128 v[40:43], v205 offset:13120
	s_waitcnt lgkmcnt(0)
	v_mfma_f32_16x16x32_bf16 v[44:47], v[222:225], v[40:43], v[44:47]
	v_mfma_f32_16x16x32_bf16 v[40:43], v[238:241], v[40:43], v[48:51]
	s_nop 2
	ds_read_b128 v[48:51], v205 offset:17472
	s_waitcnt lgkmcnt(0)
	v_mfma_f32_16x16x32_bf16 v[54:57], v[222:225], v[48:51], v[54:57]
	v_mfma_f32_16x16x32_bf16 v[48:51], v[238:241], v[48:51], v[58:61]
	s_nop 2
	ds_read_b128 v[58:61], v205 offset:21824
	s_waitcnt lgkmcnt(0)
	v_mfma_f32_16x16x32_bf16 v[62:65], v[222:225], v[58:61], v[62:65]
	v_mfma_f32_16x16x32_bf16 v[58:61], v[238:241], v[58:61], v[66:69]
	s_nop 2
	ds_read_b128 v[66:69], v202 offset:64
	s_waitcnt lgkmcnt(0)
	v_mfma_f32_16x16x32_bf16 v[206:209], v[222:225], v[66:69], v[206:209]
	v_mfma_f32_16x16x32_bf16 v[0:3], v[238:241], v[66:69], v[0:3]
	ds_read_b128 v[66:69], v52 offset:128
	s_waitcnt vmcnt(0) lgkmcnt(0)
	v_mfma_f32_16x16x32_bf16 v[8:11], v[226:229], v[66:69], v[8:11]
	v_mfma_f32_16x16x32_bf16 v[12:15], v[242:245], v[66:69], v[12:15]
	ds_read_b128 v[66:69], v205 offset:128
	s_waitcnt lgkmcnt(0)
	v_mfma_f32_16x16x32_bf16 v[20:23], v[226:229], v[66:69], v[20:23]
	v_mfma_f32_16x16x32_bf16 v[16:19], v[242:245], v[66:69], v[16:19]
	ds_read_b128 v[66:69], v205 offset:4480
	s_waitcnt lgkmcnt(0)
	v_mfma_f32_16x16x32_bf16 v[28:31], v[226:229], v[66:69], v[28:31]
	v_mfma_f32_16x16x32_bf16 v[24:27], v[242:245], v[66:69], v[24:27]
	ds_read_b128 v[66:69], v203 offset:128
	s_waitcnt lgkmcnt(0)
	v_mfma_f32_16x16x32_bf16 v[36:39], v[226:229], v[66:69], v[36:39]
	v_mfma_f32_16x16x32_bf16 v[32:35], v[242:245], v[66:69], v[32:35]
	ds_read_b128 v[66:69], v205 offset:13184
	s_waitcnt lgkmcnt(0)
	v_mfma_f32_16x16x32_bf16 v[44:47], v[226:229], v[66:69], v[44:47]
	v_mfma_f32_16x16x32_bf16 v[40:43], v[242:245], v[66:69], v[40:43]
	ds_read_b128 v[66:69], v205 offset:17536
	s_waitcnt lgkmcnt(0)
	v_mfma_f32_16x16x32_bf16 v[54:57], v[226:229], v[66:69], v[54:57]
	v_mfma_f32_16x16x32_bf16 v[66:69], v[242:245], v[66:69], v[48:51]
	s_nop 2
	ds_read_b128 v[48:51], v205 offset:21888
	s_waitcnt lgkmcnt(0)
	v_mfma_f32_16x16x32_bf16 v[62:65], v[226:229], v[48:51], v[62:65]
	v_mfma_f32_16x16x32_bf16 v[58:61], v[242:245], v[48:51], v[58:61]
	v_mfma_f32_16x16x32_bf16 v[48:51], v[226:229], v[214:217], v[206:209]
	ds_read_b128 v[210:213], v52 offset:192
	s_nop 1
	v_mfma_f32_16x16x32_bf16 v[72:75], v[242:245], v[214:217], v[0:3]
	s_waitcnt vmcnt(0) lgkmcnt(0)
	v_mfma_f32_16x16x32_bf16 v[0:3], v[230:233], v[210:213], v[8:11]
	s_nop 2
	ds_read_b128 v[8:11], v205 offset:192
	v_mfma_f32_16x16x32_bf16 v[4:7], v[246:249], v[210:213], v[12:15]
	s_waitcnt lgkmcnt(0)
	v_mfma_f32_16x16x32_bf16 v[210:213], v[230:233], v[8:11], v[20:23]
	s_nop 0
	ds_read_b128 v[12:15], v205 offset:4544
	s_nop 0
	ds_read_b128 v[20:23], v203 offset:192
	v_mfma_f32_16x16x32_bf16 v[8:11], v[246:249], v[8:11], v[16:19]
	s_waitcnt lgkmcnt(1)
	v_mfma_f32_16x16x32_bf16 v[16:19], v[230:233], v[12:15], v[28:31]
	v_mfma_f32_16x16x32_bf16 v[12:15], v[246:249], v[12:15], v[24:27]
	s_nop 1
	ds_read_b128 v[28:31], v205 offset:13248
	s_waitcnt lgkmcnt(1)
	v_mfma_f32_16x16x32_bf16 v[24:27], v[230:233], v[20:23], v[36:39]
	s_nop 2
	ds_read_b128 v[36:39], v205 offset:17600
	v_mfma_f32_16x16x32_bf16 v[20:23], v[246:249], v[20:23], v[32:35]
	s_waitcnt lgkmcnt(1)
	v_mfma_f32_16x16x32_bf16 v[32:35], v[230:233], v[28:31], v[44:47]
	v_mfma_f32_16x16x32_bf16 v[28:31], v[246:249], v[28:31], v[40:43]
	s_nop 1
	ds_read_b128 v[44:47], v205 offset:21952
	s_waitcnt lgkmcnt(1)
	v_mfma_f32_16x16x32_bf16 v[40:43], v[230:233], v[36:39], v[54:57]
	s_nop 2
	ds_read_b128 v[54:57], v202 offset:192
	v_mfma_f32_16x16x32_bf16 v[36:39], v[246:249], v[36:39], v[66:69]
	s_waitcnt lgkmcnt(0)
	s_barrier
	v_mfma_f32_16x16x32_bf16 v[68:71], v[230:233], v[54:57], v[48:51]
	s_nop 2
	v_mul_f32_e32 v48, v204, v173
	v_exp_f32_e32 v184, v48
	v_mfma_f32_16x16x32_bf16 v[64:67], v[230:233], v[44:47], v[62:65]
	v_mul_f32_e64 v50, v184, v212
	v_mul_f32_e64 v51, v184, v213
	v_mfma_f32_16x16x32_bf16 v[72:75], v[246:249], v[54:57], v[72:75]
	v_mul_f32_e64 v48, v184, v210
	v_mul_f32_e64 v49, v184, v211
	ds_read_b128 v[206:209], v200
	ds_read_b128 v[210:213], v200 offset:4352
	v_exp_f32_e32 v56, v53
	ds_read_b128 v[52:55], v52 offset:34816
	v_mul_f32_e32 v57, v204, v174
	v_mfma_f32_16x16x32_bf16 v[44:47], v[246:249], v[44:47], v[58:61]
	v_exp_f32_e32 v214, v57
	v_pk_mul_f32 v[2:3], v[56:57], v[2:3] op_sel_hi:[0,1]
	v_pk_mul_f32 v[0:1], v[56:57], v[0:1] op_sel_hi:[0,1]
	v_pk_mul_f32 v[10:11], v[184:185], v[10:11] op_sel_hi:[0,1]
	v_pk_mul_f32 v[8:9], v[184:185], v[8:9] op_sel_hi:[0,1]
	s_waitcnt lgkmcnt(0)
	v_mfma_f32_16x16x32_bf16 v[60:63], v[206:209], v[52:55], v[0:3]
	s_nop 2
	v_mul_f32_e64 v2, v56, v6
	v_mul_f32_e64 v3, v56, v7
	v_pk_mul_f32 v[0:1], v[56:57], v[4:5] op_sel_hi:[0,1]
	ds_read_b128 v[4:7], v205 offset:34816
	s_nop 0
	v_mfma_f32_16x16x32_bf16 v[56:59], v[210:213], v[52:55], v[0:3]
	s_nop 2
	v_mul_f32_e64 v0, v214, v16
	v_mul_f32_e64 v1, v214, v17
	v_mul_f32_e32 v16, v204, v175
	v_exp_f32_e32 v184, v16
	v_pk_mul_f32 v[2:3], v[214:215], v[18:19] op_sel_hi:[0,1]
	ds_read_b128 v[16:19], v205 offset:39168
	s_waitcnt lgkmcnt(1)
	v_mfma_f32_16x16x32_bf16 v[52:55], v[206:209], v[4:7], v[48:51]
	v_mfma_f32_16x16x32_bf16 v[48:51], v[210:213], v[4:7], v[8:11]
	v_mul_f32_e64 v6, v214, v14
	v_mul_f32_e64 v7, v214, v15
	v_pk_mul_f32 v[4:5], v[214:215], v[12:13] op_sel_hi:[0,1]
	ds_read_b128 v[12:15], v203 offset:34816
	v_pk_mul_f32 v[8:9], v[184:185], v[24:25] op_sel_hi:[0,1]
	v_mul_f32_e32 v24, v204, v176
	v_exp_f32_e32 v214, v24
	v_pk_mul_f32 v[10:11], v[184:185], v[26:27] op_sel_hi:[0,1]
	s_waitcnt lgkmcnt(1)
	v_mfma_f32_16x16x32_bf16 v[0:3], v[206:209], v[16:19], v[0:3]
	ds_read_b128 v[24:27], v205 offset:47872
	v_mfma_f32_16x16x32_bf16 v[4:7], v[210:213], v[16:19], v[4:7]
	v_mul_f32_e64 v18, v184, v22
	v_mul_f32_e64 v19, v184, v23
	v_pk_mul_f32 v[16:17], v[184:185], v[20:21] op_sel_hi:[0,1]
	v_pk_mul_f32 v[22:23], v[214:215], v[34:35] op_sel_hi:[0,1]
	s_waitcnt lgkmcnt(1)
	v_mfma_f32_16x16x32_bf16 v[8:11], v[206:209], v[12:15], v[8:11]
	v_mul_f32_e64 v20, v214, v32
	v_mul_f32_e64 v21, v214, v33
	v_mfma_f32_16x16x32_bf16 v[12:15], v[210:213], v[12:15], v[16:19]
	s_nop 2
	v_mul_f32_e32 v16, v204, v177
	v_exp_f32_e32 v34, v16
	v_pk_mul_f32 v[18:19], v[214:215], v[30:31] op_sel_hi:[0,1]
	v_pk_mul_f32 v[16:17], v[214:215], v[28:29] op_sel_hi:[0,1]
	ds_read_b128 v[30:33], v205 offset:52224
	s_waitcnt lgkmcnt(1)
	v_mfma_f32_16x16x32_bf16 v[20:23], v[206:209], v[24:27], v[20:23]
	v_mul_f32_e64 v28, v34, v42
	v_mul_f32_e64 v29, v34, v43
	v_pk_mul_f32 v[38:39], v[34:35], v[38:39] op_sel_hi:[0,1]
	v_mfma_f32_16x16x32_bf16 v[16:19], v[210:213], v[24:27], v[16:19]
	v_mul_f32_e64 v26, v34, v40
	v_mul_f32_e64 v27, v34, v41
	v_mul_f32_e32 v35, v204, v178
	v_exp_f32_e32 v184, v35
	ds_read_b128 v[40:43], v205 offset:56576
	v_pk_mul_f32 v[36:37], v[34:35], v[36:37] op_sel_hi:[0,1]
	s_waitcnt lgkmcnt(1)
	v_mfma_f32_16x16x32_bf16 v[24:27], v[206:209], v[30:33], v[26:29]
	v_mul_f32_e64 v34, v184, v66
	v_mul_f32_e64 v35, v184, v67
	v_mfma_f32_16x16x32_bf16 v[28:31], v[210:213], v[30:33], v[36:39]
	v_mul_f32_e64 v32, v184, v64
	v_mul_f32_e64 v33, v184, v65
	s_nop 0
	v_pk_mul_f32 v[36:37], v[184:185], v[46:47] op_sel_hi:[0,1]
	s_waitcnt lgkmcnt(0)
	v_mfma_f32_16x16x32_bf16 v[64:67], v[206:209], v[40:43], v[32:35]
	s_nop 2
	v_mul_f32_e64 v34, v184, v44
	v_mul_f32_e64 v35, v184, v45
	v_mul_f32_e32 v32, v204, v179
	v_exp_f32_e32 v44, v32
	v_mfma_f32_16x16x32_bf16 v[214:217], v[210:213], v[40:43], v[34:37]
	v_xor_b32_e32 v184, 32, v188
	v_pk_mul_f32 v[38:39], v[44:45], v[70:71] op_sel_hi:[0,1]
	s_nop 0
	ds_read_b128 v[32:35], v202 offset:34816
	v_pk_mul_f32 v[36:37], v[44:45], v[68:69] op_sel_hi:[0,1]
	s_waitcnt lgkmcnt(0)
	s_nop 0
	v_mfma_f32_16x16x32_bf16 v[68:71], v[206:209], v[32:35], v[36:39]
	ds_read_b128 v[206:209], v200 offset:64
	s_nop 1
	v_pk_mul_f32 v[38:39], v[44:45], v[74:75] op_sel_hi:[0,1]
	v_pk_mul_f32 v[36:37], v[44:45], v[72:73] op_sel_hi:[0,1]
	s_nop 1
	v_mfma_f32_16x16x32_bf16 v[72:75], v[210:213], v[32:35], v[36:39]
	ds_read_b128 v[32:35], v205 offset:39232
	s_waitcnt lgkmcnt(0)
	v_mfma_f32_16x16x32_bf16 v[44:47], v[206:209], v[32:35], v[0:3]
	s_nop 2
	ds_read_b128 v[0:3], v200 offset:4416
	s_waitcnt lgkmcnt(0)
	v_mfma_f32_16x16x32_bf16 v[36:39], v[0:3], v[32:35], v[4:7]
	s_nop 2
	ds_read_b128 v[4:7], v203 offset:34880
	s_waitcnt lgkmcnt(0)
	v_mfma_f32_16x16x32_bf16 v[40:43], v[206:209], v[4:7], v[8:11]
	v_mfma_f32_16x16x32_bf16 v[32:35], v[0:3], v[4:7], v[12:15]
	ds_read_b128 v[4:7], v205 offset:47936
	s_waitcnt lgkmcnt(0)
	v_mfma_f32_16x16x32_bf16 v[8:11], v[206:209], v[4:7], v[20:23]
	ds_read_b128 v[12:15], v205 offset:52288
	s_nop 1
	ds_read_b128 v[20:23], v205 offset:56640
	s_waitcnt lgkmcnt(0)
	v_mfma_f32_16x16x32_bf16 v[64:67], v[206:209], v[20:23], v[64:67]
	v_mfma_f32_16x16x32_bf16 v[210:213], v[0:3], v[20:23], v[214:217]
	ds_read_b128 v[20:23], v202 offset:34880
	v_mfma_f32_16x16x32_bf16 v[4:7], v[0:3], v[4:7], v[16:19]
	v_mfma_f32_16x16x32_bf16 v[16:19], v[206:209], v[12:15], v[24:27]
	v_mfma_f32_16x16x32_bf16 v[12:15], v[0:3], v[12:15], v[28:31]
	s_waitcnt lgkmcnt(0)
	v_mfma_f32_16x16x32_bf16 v[68:71], v[206:209], v[20:23], v[68:71]
	ds_read_b128 v[206:209], v200 offset:128
	v_mfma_f32_16x16x32_bf16 v[0:3], v[0:3], v[20:23], v[72:75]
	ds_read_b128 v[20:23], v205 offset:48000
	s_nop 1
	ds_read_b128 v[72:75], v200 offset:4480
	s_waitcnt lgkmcnt(0)
	v_mfma_f32_16x16x32_bf16 v[24:27], v[72:75], v[20:23], v[4:7]
	s_nop 2
	ds_read_b128 v[4:7], v205 offset:52352
	v_mfma_f32_16x16x32_bf16 v[28:31], v[206:209], v[20:23], v[8:11]
	s_waitcnt lgkmcnt(0)
	v_mfma_f32_16x16x32_bf16 v[20:23], v[206:209], v[4:7], v[16:19]
	v_mfma_f32_16x16x32_bf16 v[8:11], v[72:75], v[4:7], v[12:15]
	ds_read_b128 v[4:7], v205 offset:56704
	s_waitcnt lgkmcnt(0)
	v_mfma_f32_16x16x32_bf16 v[214:217], v[206:209], v[4:7], v[64:67]
	s_nop 2
	ds_read_b128 v[64:67], v200 offset:192
	v_mfma_f32_16x16x32_bf16 v[210:213], v[72:75], v[4:7], v[210:213]
	ds_read_b128 v[4:7], v202 offset:34944
	s_waitcnt lgkmcnt(0)
	v_mfma_f32_16x16x32_bf16 v[12:15], v[72:75], v[4:7], v[0:3]
	ds_read_b128 v[72:75], v202 offset:35008
	s_nop 1
	ds_read_b128 v[0:3], v205 offset:56768
	v_mfma_f32_16x16x32_bf16 v[16:19], v[206:209], v[4:7], v[68:71]
	s_nop 2
	ds_read_b128 v[68:71], v200 offset:4544
	s_waitcnt lgkmcnt(1)
	v_mfma_f32_16x16x32_bf16 v[4:7], v[64:67], v[0:3], v[214:217]
	v_mfma_f32_16x16x32_bf16 v[16:19], v[64:67], v[72:75], v[16:19]
	v_mul_f32_e32 v66, v61, v61
	v_fmac_f32_e32 v66, v60, v60
	v_fmac_f32_e32 v66, v62, v62
	v_and_b32_e32 v65, 64, v188
	v_fmac_f32_e32 v66, v63, v63
	v_xor_b32_e32 v64, 16, v188
	v_add_u32_e32 v65, 64, v65
	v_fmac_f32_e32 v66, v56, v56
	v_cmp_lt_i32_e32 vcc, v64, v65
	v_fmac_f32_e32 v66, v57, v57
	v_fmac_f32_e32 v66, v58, v58
	v_cndmask_b32_e32 v64, v188, v64, vcc
	v_lshlrev_b32_e32 v64, 2, v64
	v_fmac_f32_e32 v66, v59, v59
	ds_bpermute_b32 v67, v64, v66
	v_cmp_lt_i32_e32 vcc, v184, v65
	s_waitcnt lgkmcnt(1)
	v_mfma_f32_16x16x32_bf16 v[0:3], v[68:71], v[0:3], v[210:213]
	s_waitcnt lgkmcnt(0)
	v_add_f32_e32 v66, v66, v67
	v_cndmask_b32_e32 v65, v188, v184, vcc
	v_lshlrev_b32_e32 v65, 2, v65
	ds_bpermute_b32 v67, v65, v66
	v_mfma_f32_16x16x32_bf16 v[12:15], v[68:71], v[72:75], v[12:15]
	s_and_saveexec_b64 s[10:11], s[96:97]
	s_cbranch_execz .LBB0_242
	s_waitcnt lgkmcnt(0)
	v_add_f32_e32 v66, v66, v67
	ds_write_b32 v171, v66
